# P4 walks K downwards on its first unit (the retention columns, written last by P3, are read first)
# speedup vs baseline: 1.0172x; 1.0022x over previous
; #define PG8_WAIT_V(n) asm volatile("s_waitcnt vmcnt(" #n ")" ::: "memory")
;     __host__ __device__ bool next(int i, Unit& u) const {
;         const long L = (long)i * G + c; if (L >= nwg) return false;
;         int wgid = (int)L; { const int q = nwg / NXCD, r = nwg % NXCD, xcd = wgid % NXCD, off = wgid / NXCD; wgid = (xcd < r ? xcd * (q + 1) : r * (q + 1) + (xcd - r) * q) + off; }
;         const int nig = wgm * nN, gid = wgid / nig, fm = gid * wgm, gsz = (nM - fm) < wgm ? (nM - fm) : wgm;
;         u.pm = fm + ((wgid % nig) % gsz); u.pn = (wgid % nig) / gsz; return true;
; template <class Epi, class Sched, bool ALIGN_EPI = false, bool SP2 = false>
; __device__ __forceinline__ void gemm_phase(PG8_LAS unsigned char* lds, const Gemm g, const Sched& S, const Epi& E) {
;     ...
;     const int tid = tid_, wid = __builtin_amdgcn_readfirstlane(tid >> 6), lane = tid & 63, wr = wid >> 2, wc = wid & 3, fr = lane & 15, fq = lane >> 4;
;     const int K = g.K, nt = K / BK;
;     unsigned voffA[2], voffB[2];
; #pragma unroll
;     for (int i = 0; i < 2; ++i) { int R, C; stage_rc(tid * 16 + i * 8192, R, C); const int Rb = Epi::PERM ? ((R & ~31) + perm32(R & 31)) : R;
;         voffA[i] = (unsigned)(R * K + C) * 2u; voffB[i] = (unsigned)(Rb * K + C) * 2u; }
;     const size_t kstep = (size_t)(BK * 2);
;     const size_t hstep = (size_t)HALF * K * 2;
;     const size_t tstep = 2 * hstep;
;     const unsigned ldsw = (unsigned)wid * 1024u;
;     const int aoff = lds_byte(wr * 64 + fr, fq * 8), boff = lds_byte(wc * 32 + fr, fq * 8);
;     ...
;     Unit cur, nxt; int ui = 0;
;     if (!S.next(0, cur)) return;
;     f32x4 acc[2][2][4][2];
; #pragma unroll
;     for (int a = 0; a < 2; ++a)
; #pragma unroll
;         for (int b = 0; b < 2; ++b)
; #pragma unroll
;             for (int m = 0; m < 4; ++m)
; #pragma unroll
;                 for (int n = 0; n < 2; ++n) acc[a][b][m][n] = (f32x4){0.f, 0.f, 0.f, 0.f};
;     bf16x8 At[4][2], B0[2][2], B1[2][2];
;     const char* cA = (const char*)g.A + (size_t)cur.pm * tstep; const char* cB = (const char*)g.Bt + (size_t)cur.pn * tstep;
;     S.a_ready(cur);
;     if constexpr (SP2) {
;         PG8_STAGE(PG8_SB(0, 0), cB, voffB); PG8_STAGE(PG8_SB(0, 1), cB + hstep, voffB); PG8_STAGE(PG8_SA(0, 0), cA, voffA); PG8_STAGE(PG8_SA(0, 1), cA + hstep, voffA);
;         if (wr == 1) PG8_BAR;
;         PG8_WAIT_V(2); PG8_BAR;
.LBB0_672:
	s_cmp_lt_i32 s70, 5
	s_cselect_b64 s[4:5], -1, 0
	s_and_b64 s[6:7], s[4:5], s[0:1]
	s_andn2_b64 vcc, exec, s[6:7]
	s_cbranch_vccnz .LBB0_715
	v_writelane_b32 v253, s4, 0
	v_writelane_b32 v253, s5, 1
	v_writelane_b32 v253, s6, 2
	v_writelane_b32 v253, s7, 3
	v_writelane_b32 v253, s8, 4
	v_writelane_b32 v253, s9, 5
	v_writelane_b32 v253, s10, 6
	v_writelane_b32 v253, s11, 7
	v_writelane_b32 v253, s12, 8
	v_writelane_b32 v253, s13, 9
	v_writelane_b32 v253, s14, 10
	v_writelane_b32 v253, s15, 11
	v_writelane_b32 v253, s16, 12
	v_writelane_b32 v253, s17, 13
	v_writelane_b32 v253, s18, 14
	v_writelane_b32 v253, s19, 15
	v_writelane_b32 v253, s20, 16
	v_writelane_b32 v253, s21, 17
	v_writelane_b32 v253, s22, 18
	v_writelane_b32 v253, s23, 19
	v_writelane_b32 v253, s24, 20
	v_writelane_b32 v253, s25, 21
	v_writelane_b32 v253, s26, 22
	v_writelane_b32 v253, s27, 23
	v_writelane_b32 v253, s28, 24
	v_writelane_b32 v253, s29, 25
	v_writelane_b32 v253, s30, 26
	v_writelane_b32 v253, s31, 27
	v_writelane_b32 v253, s32, 28
	v_writelane_b32 v253, s33, 29
	v_writelane_b32 v253, s34, 30
	v_writelane_b32 v253, s35, 31
	v_writelane_b32 v253, s36, 32
	v_writelane_b32 v253, s37, 33
	v_writelane_b32 v253, s38, 34
	v_writelane_b32 v253, s39, 35
	v_writelane_b32 v253, s40, 36
	v_writelane_b32 v253, s41, 37
	v_writelane_b32 v253, s42, 38
	v_writelane_b32 v253, s43, 39
	v_writelane_b32 v253, s44, 40
	v_writelane_b32 v253, s45, 41
	v_writelane_b32 v253, s46, 42
	v_writelane_b32 v253, s47, 43
	v_writelane_b32 v253, s48, 44
	v_writelane_b32 v253, s49, 45
	v_writelane_b32 v253, s50, 46
	v_writelane_b32 v253, s51, 47
	v_writelane_b32 v253, s52, 48
	v_writelane_b32 v253, s53, 49
	v_writelane_b32 v253, s54, 50
	v_writelane_b32 v253, s55, 51
	v_writelane_b32 v253, s56, 52
	v_writelane_b32 v253, s57, 53
	v_writelane_b32 v253, s58, 54
	v_writelane_b32 v253, s59, 55
	s_mov_b32 s40, vcc_lo
	s_mov_b32 s41, vcc_hi
	v_writelane_b32 v253, s40, 60
	v_writelane_b32 v253, s41, 61
	v_lshrrev_b32_e32 v254, 6, v185
	v_readlane_b32 s14, v244, 4
	v_readfirstlane_b32 s36, v254
	s_nop 3
	s_lshr_b32 s37, s36, 2
	s_and_b32 s38, s36, 3
	s_lshl_b32 s35, s36, 10
	s_add_u32 s10, s76, 0x18800000
	s_addc_u32 s11, s77, 0
	s_add_u32 s12, s76, 0x1d00000
	s_addc_u32 s13, s77, 0
	s_mov_b32 s16, 0
	s_mul_i32 s40, s16, s14
	s_add_u32 s40, s40, s2
	s_cmp_lt_u32 s40, 512
	s_cselect_b32 s44, 1, 0
	s_min_u32 s40, s40, 511
	s_and_b32 s41, s40, 7
	s_lshr_b32 s42, s40, 3
	s_mul_i32 s41, s41, 64
	s_add_u32 s41, s41, s42
	s_lshr_b32 s42, s41, 5
	s_and_b32 s43, s41, 31
	s_and_b32 s40, s43, 3
	s_lshl_b32 s42, s42, 2
	s_add_u32 s17, s42, s40
	s_lshr_b32 s18, s43, 2
	s_cmp_eq_u32 s44, 0
	s_cbranch_scc1 .Lp4_exit
	v_and_b32_e32 v254, 63, v185
	v_and_b32_e32 v255, 15, v254
	v_lshrrev_b32_e32 v186, 1, v255
	v_lshrrev_b32_e32 v187, 4, v254
	v_xor_b32_e32 v186, v186, v187
	v_lshlrev_b32_e32 v255, 7, v255
	v_lshl_or_b32 v255, v186, 4, v255
	s_lshl_b32 s40, s37, 13
	s_lshl_b32 s41, s38, 12
	s_add_u32 s41, s41, 0x10000
	v_add_u32_e32 v245, s40, v255
	v_add_u32_e32 v247, s41, v255
	v_xor_b32_e32 v246, 64, v245
	v_xor_b32_e32 v248, 64, v247
	v_lshrrev_b32_e32 v255, 3, v254
	v_and_b32_e32 v186, 7, v254
	s_and_b32 s40, s36, 1
	s_lshl_b32 s40, s40, 2
	v_lshrrev_b32_e32 v187, 1, v255
	v_add_u32_e32 v187, s40, v187
	v_xor_b32_e32 v186, v186, v187
	v_lshlrev_b32_e32 v186, 4, v186
	s_lshl_b32 s40, s36, 3
	v_add_u32_e32 v187, s40, v255
	v_mul_u32_u24_e32 v187, 0x1000, v187
	v_add_u32_e32 v249, v187, v186
	v_add_u32_e32 v250, 0x40000, v249
	s_and_b32 s40, s36, 3
	s_lshl_b32 s40, s40, 3
	v_add_u32_e32 v187, s40, v255
	v_lshrrev_b32_e32 v254, 4, v187
	v_lshlrev_b32_e32 v254, 2, v254
	v_and_b32_e32 v255, 3, v187
	v_add_u32_e32 v254, v254, v255
	v_and_b32_e32 v187, 12, v187
	v_lshl_add_u32 v254, v187, 1, v254
	s_lshr_b32 s40, s36, 2
	s_lshl_b32 s40, s40, 5
	v_add_u32_e32 v254, s40, v254
	v_mul_u32_u24_e32 v254, 0x1000, v254
	v_add_u32_e32 v251, v254, v186
	v_add_u32_e32 v252, 0x40000, v251
	s_mul_i32 s40, s17, 0x100000
	s_add_u32 s22, s10, s40
	s_addc_u32 s23, s11, 0
	s_mul_i32 s40, s18, 0x100000
	s_add_u32 s24, s12, s40
	s_addc_u32 s25, s13, 0
	s_and_b32 s40, s16, 1
	s_xor_b32 s40, s40, 1
	s_lshl_b32 s4, s40, 8
	s_sub_u32 s4, 128, s4
	s_sub_u32 s5, 0, s40
	s_mul_i32 s8, s40, 3968
	s_add_u32 s30, s22, s8
	s_addc_u32 s31, s23, 0
	s_add_u32 s32, s24, s8
	s_addc_u32 s33, s25, 0
	s_add_u32 s56, s30, 0x80000
	s_addc_u32 s57, s31, 0
	s_add_u32 s58, s32, 0x80000
	s_addc_u32 s59, s33, 0
	s_add_i32 m0, s35, 0x0
	s_nop 0
	global_load_lds_dwordx4 v249, s[30:31]
	s_add_i32 m0, s35, 0x2000
	s_nop 0
	global_load_lds_dwordx4 v250, s[30:31]
	s_add_i32 m0, s35, 0x10000
	s_nop 0
	global_load_lds_dwordx4 v251, s[32:33]
	s_add_i32 m0, s35, 0x12000
	s_nop 0
	global_load_lds_dwordx4 v252, s[32:33]
	s_add_i32 m0, s35, 0x4000
	s_nop 0
	global_load_lds_dwordx4 v249, s[56:57]
	s_add_i32 m0, s35, 0x6000
	s_nop 0
	global_load_lds_dwordx4 v250, s[56:57]
	s_add_i32 m0, s35, 0x14000
	s_nop 0
	global_load_lds_dwordx4 v251, s[58:59]
	s_add_i32 m0, s35, 0x16000
	s_nop 0
	global_load_lds_dwordx4 v252, s[58:59]
	s_add_u32 s30, s30, s4
	s_addc_u32 s31, s31, s5
	s_add_u32 s56, s56, s4
	s_addc_u32 s57, s57, s5
	s_add_u32 s32, s32, s4
	s_addc_u32 s33, s33, s5
	s_add_u32 s58, s58, s4
	s_addc_u32 s59, s59, s5
	s_add_i32 m0, s35, 0x8000
	s_nop 0
	global_load_lds_dwordx4 v249, s[30:31]
	s_add_i32 m0, s35, 0xa000
	s_nop 0
	global_load_lds_dwordx4 v250, s[30:31]
	s_add_i32 m0, s35, 0x1c000
	s_nop 0
	global_load_lds_dwordx4 v251, s[58:59]
	s_add_i32 m0, s35, 0x1e000
	s_nop 0
	global_load_lds_dwordx4 v252, s[58:59]
	s_add_i32 m0, s35, 0xc000
	s_nop 0
	global_load_lds_dwordx4 v249, s[56:57]
	s_add_i32 m0, s35, 0xe000
	s_nop 0
	global_load_lds_dwordx4 v250, s[56:57]
	s_add_i32 m0, s35, 0x18000
	s_nop 0
	global_load_lds_dwordx4 v251, s[32:33]
	s_add_i32 m0, s35, 0x1a000
	s_nop 0
	global_load_lds_dwordx4 v252, s[32:33]
	s_add_u32 s30, s30, s4
	s_addc_u32 s31, s31, s5
	s_add_u32 s56, s56, s4
	s_addc_u32 s57, s57, s5
	s_add_u32 s32, s32, s4
	s_addc_u32 s33, s33, s5
	s_add_u32 s58, s58, s4
	s_addc_u32 s59, s59, s5
	s_waitcnt vmcnt(12)
	s_barrier

; #define PG8_STAGE(bufoff, gbase, voff) do { _Pragma("unroll") for (int _i = 0; _i < 2; ++_i) \
;         __builtin_amdgcn_global_load_lds((const unsigned*)((const char*)(gbase) + (voff)[_i]), (PG8_LAS unsigned*)(lds + (bufoff) + ldsw + _i * 8192), 16, 0, 0); } while (0)
; #define PG8_LDA(dst, b, h) do { _Pragma("unroll") for (int m = 0; m < 4; ++m) _Pragma("unroll") for (int k = 0; k < 2; ++k) dst[m][k] = *(const PG8_LAS bf16x8*)(lds + PG8_SA(b, h) + aoff + m * 2048 + k * 1024); } while (0)
; #define PG8_LDB(dst, b, h) do { _Pragma("unroll") for (int n = 0; n < 2; ++n) _Pragma("unroll") for (int k = 0; k < 2; ++k) dst[n][k] = *(const PG8_LAS bf16x8*)(lds + PG8_SB(b, h) + boff + n * 2048 + k * 1024); } while (0)
; #define PG8_MMA(ai, bj, At, Bt) do { __builtin_amdgcn_s_setprio(1); _Pragma("unroll") for (int m = 0; m < 4; ++m) _Pragma("unroll") for (int n = 0; n < 2; ++n) _Pragma("unroll") for (int k = 0; k < 2; ++k) \
;         acc[ai][bj][m][n] = __builtin_amdgcn_mfma_f32_16x16x32_bf16(Bt[n][k], At[m][k], acc[ai][bj][m][n], 0, 0, 0); __builtin_amdgcn_s_setprio(0); } while (0)
; #define PG8_WAIT_V(n) asm volatile("s_waitcnt vmcnt(" #n ")" ::: "memory")
; template <class Epi, class Sched, bool ALIGN_EPI = false, bool SP2 = false>
; __device__ __forceinline__ void gemm_phase(PG8_LAS unsigned char* lds, const Gemm g, const Sched& S, const Epi& E) {
;     ...
;             PG8_LDB(B0, 0, 0); PG8_LDB(B1, 0, 1); PG8_SCHED; PG8_LDA(At, 0, 0); PG8_STAGE(PG8_SA(1, 1), a1 + hstep, voffA);
;             PG8_WAIT_V(8); PG8_WAIT_L(0); PG8_BAR; PG8_MMA(0, 0, At, B0); PG8_MMA(0, 1, At, B1); PG8_BAR; PG8_SCHED;
;             PG8_LDA(At, 0, 1); PG8_STAGE(PG8_SB(0, 0), b2, voffB); PG8_STAGE(PG8_SB(0, 1), b2 + hstep, voffB); PG8_STAGE(PG8_SA(0, 0), a2, voffA);
;             PG8_WAIT_V(8); PG8_WAIT_L(0); PG8_BAR; PG8_MMA(1, 0, At, B0); PG8_MMA(1, 1, At, B1); PG8_BAR; PG8_SCHED;
;             PG8_LDB(B0, 1, 0); PG8_LDB(B1, 1, 1); PG8_SCHED; PG8_LDA(At, 1, 0); PG8_STAGE(PG8_SA(0, 1), a2 + hstep, voffA);
;             PG8_WAIT_V(8); PG8_WAIT_L(0); PG8_BAR; PG8_MMA(0, 0, At, B0); PG8_MMA(0, 1, At, B1); PG8_BAR; PG8_SCHED;
;             PG8_LDA(At, 1, 1); PG8_STAGE(PG8_SB(1, 0), b3, voffB); PG8_STAGE(PG8_SB(1, 1), b3 + hstep, voffB); PG8_STAGE(PG8_SA(1, 0), a3, voffA);
;             PG8_WAIT_V(8); PG8_WAIT_L(0); PG8_BAR; PG8_MMA(1, 0, At, B0); PG8_MMA(1, 1, At, B1); PG8_BAR; PG8_SCHED;
.Lp4_kloop0:
	s_waitcnt vmcnt(8)
	s_waitcnt lgkmcnt(0)
	s_barrier
	v_mfma_f32_16x16x32_bf16 v[0:3], v[196:199], v[128:131], v[0:3]
	ds_read_b128 v[212:215], v247 offset:16384
	v_mfma_f32_16x16x32_bf16 v[0:3], v[200:203], v[132:135], v[0:3]
	ds_read_b128 v[216:219], v248 offset:16384
	v_mfma_f32_16x16x32_bf16 v[4:7], v[208:211], v[132:135], v[4:7]
	ds_read_b128 v[220:223], v247 offset:18432
	v_mfma_f32_16x16x32_bf16 v[4:7], v[204:207], v[128:131], v[4:7]
	ds_read_b128 v[224:227], v248 offset:18432
	v_mfma_f32_16x16x32_bf16 v[12:15], v[204:207], v[136:139], v[12:15]
	s_add_i32 m0, s35, 0x0
	v_mfma_f32_16x16x32_bf16 v[12:15], v[208:211], v[140:143], v[12:15]
	global_load_lds_dwordx4 v249, s[30:31]
	v_mfma_f32_16x16x32_bf16 v[8:11], v[200:203], v[140:143], v[8:11]
	s_add_i32 m0, s35, 0x2000
	v_mfma_f32_16x16x32_bf16 v[8:11], v[196:199], v[136:139], v[8:11]
	global_load_lds_dwordx4 v250, s[30:31]
	v_mfma_f32_16x16x32_bf16 v[16:19], v[196:199], v[144:147], v[16:19]
	s_add_i32 m0, s35, 0x10000
	v_mfma_f32_16x16x32_bf16 v[16:19], v[200:203], v[148:151], v[16:19]
	global_load_lds_dwordx4 v251, s[32:33]
	v_mfma_f32_16x16x32_bf16 v[20:23], v[208:211], v[148:151], v[20:23]
	s_add_i32 m0, s35, 0x12000
	v_mfma_f32_16x16x32_bf16 v[20:23], v[204:207], v[144:147], v[20:23]
	global_load_lds_dwordx4 v252, s[32:33]
	v_mfma_f32_16x16x32_bf16 v[28:31], v[204:207], v[152:155], v[28:31]
	ds_read_b128 v[160:163], v245 offset:16384
	v_mfma_f32_16x16x32_bf16 v[28:31], v[208:211], v[156:159], v[28:31]
	ds_read_b128 v[164:167], v246 offset:16384
	v_mfma_f32_16x16x32_bf16 v[24:27], v[200:203], v[156:159], v[24:27]
	ds_read_b128 v[168:171], v245 offset:18432
	v_mfma_f32_16x16x32_bf16 v[24:27], v[196:199], v[152:155], v[24:27]
	ds_read_b128 v[172:175], v246 offset:18432
	s_waitcnt lgkmcnt(4)
	v_mfma_f32_16x16x32_bf16 v[32:35], v[212:215], v[128:131], v[32:35]
	ds_read_b128 v[176:179], v245 offset:20480
	v_mfma_f32_16x16x32_bf16 v[32:35], v[216:219], v[132:135], v[32:35]
	ds_read_b128 v[180:183], v246 offset:20480
	v_mfma_f32_16x16x32_bf16 v[36:39], v[224:227], v[132:135], v[36:39]
	ds_read_b128 v[188:191], v245 offset:22528
	v_mfma_f32_16x16x32_bf16 v[36:39], v[220:223], v[128:131], v[36:39]
	ds_read_b128 v[192:195], v246 offset:22528
	v_mfma_f32_16x16x32_bf16 v[44:47], v[220:223], v[136:139], v[44:47]
	v_mfma_f32_16x16x32_bf16 v[44:47], v[224:227], v[140:143], v[44:47]
	v_mfma_f32_16x16x32_bf16 v[40:43], v[216:219], v[140:143], v[40:43]
	v_mfma_f32_16x16x32_bf16 v[40:43], v[212:215], v[136:139], v[40:43]
	v_mfma_f32_16x16x32_bf16 v[48:51], v[212:215], v[144:147], v[48:51]
	v_mfma_f32_16x16x32_bf16 v[48:51], v[216:219], v[148:151], v[48:51]
	v_mfma_f32_16x16x32_bf16 v[52:55], v[224:227], v[148:151], v[52:55]
	v_mfma_f32_16x16x32_bf16 v[52:55], v[220:223], v[144:147], v[52:55]
	v_mfma_f32_16x16x32_bf16 v[60:63], v[220:223], v[152:155], v[60:63]
	v_mfma_f32_16x16x32_bf16 v[60:63], v[224:227], v[156:159], v[60:63]
	v_mfma_f32_16x16x32_bf16 v[56:59], v[216:219], v[156:159], v[56:59]
	v_mfma_f32_16x16x32_bf16 v[56:59], v[212:215], v[152:155], v[56:59]
	s_waitcnt vmcnt(8)
	s_waitcnt lgkmcnt(0)
	s_barrier
	v_mfma_f32_16x16x32_bf16 v[96:99], v[212:215], v[160:163], v[96:99]
	s_add_i32 m0, s35, 0x4000
	v_mfma_f32_16x16x32_bf16 v[96:99], v[216:219], v[164:167], v[96:99]
	global_load_lds_dwordx4 v249, s[56:57]
	v_mfma_f32_16x16x32_bf16 v[100:103], v[224:227], v[164:167], v[100:103]
	s_add_i32 m0, s35, 0x6000
	v_mfma_f32_16x16x32_bf16 v[100:103], v[220:223], v[160:163], v[100:103]
	global_load_lds_dwordx4 v250, s[56:57]
	v_mfma_f32_16x16x32_bf16 v[108:111], v[220:223], v[168:171], v[108:111]
	s_add_i32 m0, s35, 0x14000
	v_mfma_f32_16x16x32_bf16 v[108:111], v[224:227], v[172:175], v[108:111]
	global_load_lds_dwordx4 v251, s[58:59]
	v_mfma_f32_16x16x32_bf16 v[104:107], v[216:219], v[172:175], v[104:107]
	s_add_i32 m0, s35, 0x16000
	v_mfma_f32_16x16x32_bf16 v[104:107], v[212:215], v[168:171], v[104:107]
	global_load_lds_dwordx4 v252, s[58:59]
	v_mfma_f32_16x16x32_bf16 v[112:115], v[212:215], v[176:179], v[112:115]
	ds_read_b128 v[128:131], v245 offset:32768
	v_mfma_f32_16x16x32_bf16 v[112:115], v[216:219], v[180:183], v[112:115]
	ds_read_b128 v[132:135], v246 offset:32768
	v_mfma_f32_16x16x32_bf16 v[116:119], v[224:227], v[180:183], v[116:119]
	ds_read_b128 v[136:139], v245 offset:34816
	v_mfma_f32_16x16x32_bf16 v[116:119], v[220:223], v[176:179], v[116:119]
	ds_read_b128 v[140:143], v246 offset:34816
	v_mfma_f32_16x16x32_bf16 v[124:127], v[220:223], v[188:191], v[124:127]
	ds_read_b128 v[144:147], v245 offset:36864
	v_mfma_f32_16x16x32_bf16 v[124:127], v[224:227], v[192:195], v[124:127]
	ds_read_b128 v[148:151], v246 offset:36864
	v_mfma_f32_16x16x32_bf16 v[120:123], v[216:219], v[192:195], v[120:123]
	ds_read_b128 v[152:155], v245 offset:38912
	v_mfma_f32_16x16x32_bf16 v[120:123], v[212:215], v[188:191], v[120:123]
	ds_read_b128 v[156:159], v246 offset:38912
	v_mfma_f32_16x16x32_bf16 v[64:67], v[196:199], v[160:163], v[64:67]
	ds_read_b128 v[212:215], v247 offset:49152
	v_mfma_f32_16x16x32_bf16 v[64:67], v[200:203], v[164:167], v[64:67]
	ds_read_b128 v[216:219], v248 offset:49152
	v_mfma_f32_16x16x32_bf16 v[68:71], v[208:211], v[164:167], v[68:71]
	ds_read_b128 v[220:223], v247 offset:51200
	v_mfma_f32_16x16x32_bf16 v[68:71], v[204:207], v[160:163], v[68:71]
	ds_read_b128 v[224:227], v248 offset:51200
	v_mfma_f32_16x16x32_bf16 v[76:79], v[204:207], v[168:171], v[76:79]
	s_add_u32 s30, s30, s4
	s_addc_u32 s31, s31, s5
	s_add_u32 s56, s56, s4
	s_addc_u32 s57, s57, s5
	v_mfma_f32_16x16x32_bf16 v[76:79], v[208:211], v[172:175], v[76:79]
	s_add_u32 s32, s32, s4
	s_addc_u32 s33, s33, s5
	s_add_u32 s58, s58, s4
	s_addc_u32 s59, s59, s5
	v_mfma_f32_16x16x32_bf16 v[72:75], v[200:203], v[172:175], v[72:75]
	v_mfma_f32_16x16x32_bf16 v[72:75], v[196:199], v[168:171], v[72:75]
	v_mfma_f32_16x16x32_bf16 v[80:83], v[196:199], v[176:179], v[80:83]
	v_mfma_f32_16x16x32_bf16 v[80:83], v[200:203], v[180:183], v[80:83]
	v_mfma_f32_16x16x32_bf16 v[84:87], v[208:211], v[180:183], v[84:87]
	v_mfma_f32_16x16x32_bf16 v[84:87], v[204:207], v[176:179], v[84:87]
	v_mfma_f32_16x16x32_bf16 v[92:95], v[204:207], v[188:191], v[92:95]
	v_mfma_f32_16x16x32_bf16 v[92:95], v[208:211], v[192:195], v[92:95]
	v_mfma_f32_16x16x32_bf16 v[88:91], v[200:203], v[192:195], v[88:91]
	v_mfma_f32_16x16x32_bf16 v[88:91], v[196:199], v[188:191], v[88:91]
	s_waitcnt vmcnt(8)
	s_waitcnt lgkmcnt(0)
	s_barrier
; #define PG8_STAGE(bufoff, gbase, voff) do { _Pragma("unroll") for (int _i = 0; _i < 2; ++_i) \
;         __builtin_amdgcn_global_load_lds((const unsigned*)((const char*)(gbase) + (voff)[_i]), (PG8_LAS unsigned*)(lds + (bufoff) + ldsw + _i * 8192), 16, 0, 0); } while (0)
; #define PG8_LDA(dst, b, h) do { _Pragma("unroll") for (int m = 0; m < 4; ++m) _Pragma("unroll") for (int k = 0; k < 2; ++k) dst[m][k] = *(const PG8_LAS bf16x8*)(lds + PG8_SA(b, h) + aoff + m * 2048 + k * 1024); } while (0)
; #define PG8_WAIT_V(n) asm volatile("s_waitcnt vmcnt(" #n ")" ::: "memory")
; template <class Epi, class Sched, bool ALIGN_EPI = false, bool SP2 = false>
; __device__ __forceinline__ void gemm_phase(PG8_LAS unsigned char* lds, const Gemm g, const Sched& S, const Epi& E) {
;     ...
;         const bool has_next = S.next(ui + 1, nxt);
;         const char* nA = has_next ? (const char*)g.A + (size_t)nxt.pm * tstep : cA; const char* nB = has_next ? (const char*)g.Bt + (size_t)nxt.pn * tstep : cB;
;         for (int t = 0; t < nt; t += 2) {
;             const bool last = (t == nt - 2);
;             const char* a1 = cA + (size_t)(t + 1) * kstep;
;             const char* a2 = last ? nA : cA + (size_t)(t + 2) * kstep; const char* b2 = last ? nB : cB + (size_t)(t + 2) * kstep;
;             const char* a3 = a2 + kstep; const char* b3 = b2 + kstep;
;     ...
;             PG8_LDB(B0, 0, 0); PG8_LDB(B1, 0, 1); PG8_SCHED; PG8_LDA(At, 0, 0); PG8_STAGE(PG8_SA(1, 1), a1 + hstep, voffA);
;             PG8_WAIT_V(8); PG8_WAIT_L(0); PG8_BAR; PG8_MMA(0, 0, At, B0); PG8_MMA(0, 1, At, B1); PG8_BAR; PG8_SCHED;
;             PG8_LDA(At, 0, 1); PG8_STAGE(PG8_SB(0, 0), b2, voffB); PG8_STAGE(PG8_SB(0, 1), b2 + hstep, voffB); PG8_STAGE(PG8_SA(0, 0), a2, voffA);
;             PG8_WAIT_V(8); PG8_WAIT_L(0); PG8_BAR; PG8_MMA(1, 0, At, B0); PG8_MMA(1, 1, At, B1); PG8_BAR; PG8_SCHED;
;             PG8_LDB(B0, 1, 0); PG8_LDB(B1, 1, 1); PG8_SCHED; PG8_LDA(At, 1, 0); PG8_STAGE(PG8_SA(0, 1), a2 + hstep, voffA);
;             PG8_WAIT_V(8); PG8_WAIT_L(0); PG8_BAR; PG8_MMA(0, 0, At, B0); PG8_MMA(0, 1, At, B1); PG8_BAR; PG8_SCHED;
;             PG8_LDA(At, 1, 1); PG8_STAGE(PG8_SB(1, 0), b3, voffB); PG8_STAGE(PG8_SB(1, 1), b3 + hstep, voffB); PG8_STAGE(PG8_SA(1, 0), a3, voffA);
;             PG8_WAIT_V(8); PG8_WAIT_L(0); PG8_BAR; PG8_MMA(1, 0, At, B0); PG8_MMA(1, 1, At, B1); PG8_BAR; PG8_SCHED;
	v_mfma_f32_16x16x32_bf16 v[32:35], v[212:215], v[128:131], v[32:35]
	ds_read_b128 v[196:199], v247 offset:32768
	v_mfma_f32_16x16x32_bf16 v[32:35], v[216:219], v[132:135], v[32:35]
	ds_read_b128 v[200:203], v248 offset:32768
	v_mfma_f32_16x16x32_bf16 v[36:39], v[224:227], v[132:135], v[36:39]
	ds_read_b128 v[204:207], v247 offset:34816
	v_mfma_f32_16x16x32_bf16 v[36:39], v[220:223], v[128:131], v[36:39]
	ds_read_b128 v[208:211], v248 offset:34816
	v_mfma_f32_16x16x32_bf16 v[44:47], v[220:223], v[136:139], v[44:47]
	s_add_i32 m0, s35, 0x8000
	v_mfma_f32_16x16x32_bf16 v[44:47], v[224:227], v[140:143], v[44:47]
	global_load_lds_dwordx4 v249, s[30:31]
	v_mfma_f32_16x16x32_bf16 v[40:43], v[216:219], v[140:143], v[40:43]
	s_add_i32 m0, s35, 0xa000
	v_mfma_f32_16x16x32_bf16 v[40:43], v[212:215], v[136:139], v[40:43]
	global_load_lds_dwordx4 v250, s[30:31]
	v_mfma_f32_16x16x32_bf16 v[48:51], v[212:215], v[144:147], v[48:51]
	s_add_i32 m0, s35, 0x1c000
	v_mfma_f32_16x16x32_bf16 v[48:51], v[216:219], v[148:151], v[48:51]
	global_load_lds_dwordx4 v251, s[58:59]
	v_mfma_f32_16x16x32_bf16 v[52:55], v[224:227], v[148:151], v[52:55]
	s_add_i32 m0, s35, 0x1e000
	v_mfma_f32_16x16x32_bf16 v[52:55], v[220:223], v[144:147], v[52:55]
	global_load_lds_dwordx4 v252, s[58:59]
	v_mfma_f32_16x16x32_bf16 v[60:63], v[220:223], v[152:155], v[60:63]
	ds_read_b128 v[160:163], v245 offset:49152
	v_mfma_f32_16x16x32_bf16 v[60:63], v[224:227], v[156:159], v[60:63]
	ds_read_b128 v[164:167], v246 offset:49152
	v_mfma_f32_16x16x32_bf16 v[56:59], v[216:219], v[156:159], v[56:59]
	ds_read_b128 v[168:171], v245 offset:51200
	v_mfma_f32_16x16x32_bf16 v[56:59], v[212:215], v[152:155], v[56:59]
	ds_read_b128 v[172:175], v246 offset:51200
	s_waitcnt lgkmcnt(4)
	v_mfma_f32_16x16x32_bf16 v[0:3], v[196:199], v[128:131], v[0:3]
	ds_read_b128 v[176:179], v245 offset:53248
	v_mfma_f32_16x16x32_bf16 v[0:3], v[200:203], v[132:135], v[0:3]
	ds_read_b128 v[180:183], v246 offset:53248
	v_mfma_f32_16x16x32_bf16 v[4:7], v[208:211], v[132:135], v[4:7]
	ds_read_b128 v[188:191], v245 offset:55296
	v_mfma_f32_16x16x32_bf16 v[4:7], v[204:207], v[128:131], v[4:7]
	ds_read_b128 v[192:195], v246 offset:55296
	v_mfma_f32_16x16x32_bf16 v[12:15], v[204:207], v[136:139], v[12:15]
	v_mfma_f32_16x16x32_bf16 v[12:15], v[208:211], v[140:143], v[12:15]
	v_mfma_f32_16x16x32_bf16 v[8:11], v[200:203], v[140:143], v[8:11]
	v_mfma_f32_16x16x32_bf16 v[8:11], v[196:199], v[136:139], v[8:11]
	v_mfma_f32_16x16x32_bf16 v[16:19], v[196:199], v[144:147], v[16:19]
	v_mfma_f32_16x16x32_bf16 v[16:19], v[200:203], v[148:151], v[16:19]
	v_mfma_f32_16x16x32_bf16 v[20:23], v[208:211], v[148:151], v[20:23]
	v_mfma_f32_16x16x32_bf16 v[20:23], v[204:207], v[144:147], v[20:23]
	v_mfma_f32_16x16x32_bf16 v[28:31], v[204:207], v[152:155], v[28:31]
	v_mfma_f32_16x16x32_bf16 v[28:31], v[208:211], v[156:159], v[28:31]
	v_mfma_f32_16x16x32_bf16 v[24:27], v[200:203], v[156:159], v[24:27]
	v_mfma_f32_16x16x32_bf16 v[24:27], v[196:199], v[152:155], v[24:27]
	s_waitcnt vmcnt(8)
	s_waitcnt lgkmcnt(0)
	s_barrier
	v_mfma_f32_16x16x32_bf16 v[64:67], v[196:199], v[160:163], v[64:67]
	s_add_i32 m0, s35, 0xc000
	v_mfma_f32_16x16x32_bf16 v[64:67], v[200:203], v[164:167], v[64:67]
	global_load_lds_dwordx4 v249, s[56:57]
	v_mfma_f32_16x16x32_bf16 v[68:71], v[208:211], v[164:167], v[68:71]
	s_add_i32 m0, s35, 0xe000
	v_mfma_f32_16x16x32_bf16 v[68:71], v[204:207], v[160:163], v[68:71]
	global_load_lds_dwordx4 v250, s[56:57]
	v_mfma_f32_16x16x32_bf16 v[76:79], v[204:207], v[168:171], v[76:79]
	s_add_i32 m0, s35, 0x18000
	v_mfma_f32_16x16x32_bf16 v[76:79], v[208:211], v[172:175], v[76:79]
	global_load_lds_dwordx4 v251, s[32:33]
	v_mfma_f32_16x16x32_bf16 v[72:75], v[200:203], v[172:175], v[72:75]
	s_add_i32 m0, s35, 0x1a000
	v_mfma_f32_16x16x32_bf16 v[72:75], v[196:199], v[168:171], v[72:75]
	global_load_lds_dwordx4 v252, s[32:33]
	v_mfma_f32_16x16x32_bf16 v[80:83], v[196:199], v[176:179], v[80:83]
	ds_read_b128 v[128:131], v245 offset:0
	v_mfma_f32_16x16x32_bf16 v[80:83], v[200:203], v[180:183], v[80:83]
	ds_read_b128 v[132:135], v246 offset:0
	v_mfma_f32_16x16x32_bf16 v[84:87], v[208:211], v[180:183], v[84:87]
	ds_read_b128 v[136:139], v245 offset:2048
	v_mfma_f32_16x16x32_bf16 v[84:87], v[204:207], v[176:179], v[84:87]
	ds_read_b128 v[140:143], v246 offset:2048
	v_mfma_f32_16x16x32_bf16 v[92:95], v[204:207], v[188:191], v[92:95]
	ds_read_b128 v[144:147], v245 offset:4096
	v_mfma_f32_16x16x32_bf16 v[92:95], v[208:211], v[192:195], v[92:95]
	ds_read_b128 v[148:151], v246 offset:4096
	v_mfma_f32_16x16x32_bf16 v[88:91], v[200:203], v[192:195], v[88:91]
	ds_read_b128 v[152:155], v245 offset:6144
	v_mfma_f32_16x16x32_bf16 v[88:91], v[196:199], v[188:191], v[88:91]
	ds_read_b128 v[156:159], v246 offset:6144
	v_mfma_f32_16x16x32_bf16 v[96:99], v[212:215], v[160:163], v[96:99]
	ds_read_b128 v[196:199], v247 offset:0
	v_mfma_f32_16x16x32_bf16 v[96:99], v[216:219], v[164:167], v[96:99]
	ds_read_b128 v[200:203], v248 offset:0
	v_mfma_f32_16x16x32_bf16 v[100:103], v[224:227], v[164:167], v[100:103]
	ds_read_b128 v[204:207], v247 offset:2048
	v_mfma_f32_16x16x32_bf16 v[100:103], v[220:223], v[160:163], v[100:103]
	ds_read_b128 v[208:211], v248 offset:2048
	v_mfma_f32_16x16x32_bf16 v[108:111], v[220:223], v[168:171], v[108:111]
	s_add_u32 s30, s30, s4
	s_addc_u32 s31, s31, s5
	s_add_u32 s56, s56, s4
	s_addc_u32 s57, s57, s5
	v_mfma_f32_16x16x32_bf16 v[108:111], v[224:227], v[172:175], v[108:111]
	s_add_u32 s32, s32, s4
	s_addc_u32 s33, s33, s5
	s_add_u32 s58, s58, s4
	s_addc_u32 s59, s59, s5
	v_mfma_f32_16x16x32_bf16 v[104:107], v[216:219], v[172:175], v[104:107]
	v_mfma_f32_16x16x32_bf16 v[104:107], v[212:215], v[168:171], v[104:107]
	v_mfma_f32_16x16x32_bf16 v[112:115], v[212:215], v[176:179], v[112:115]
	v_mfma_f32_16x16x32_bf16 v[112:115], v[216:219], v[180:183], v[112:115]
	v_mfma_f32_16x16x32_bf16 v[116:119], v[224:227], v[180:183], v[116:119]
	v_mfma_f32_16x16x32_bf16 v[116:119], v[220:223], v[176:179], v[116:119]
	v_mfma_f32_16x16x32_bf16 v[124:127], v[220:223], v[188:191], v[124:127]
	v_mfma_f32_16x16x32_bf16 v[124:127], v[224:227], v[192:195], v[124:127]
	v_mfma_f32_16x16x32_bf16 v[120:123], v[216:219], v[192:195], v[120:123]
	v_mfma_f32_16x16x32_bf16 v[120:123], v[212:215], v[188:191], v[120:123]
	s_add_i32 s34, s34, -1
	s_cmp_lg_u32 s34, 1
	s_cbranch_scc1 .Lp4_nosw0
	s_add_u32 s45, s16, 1
	s_and_b32 s40, s45, 1
	s_xor_b32 s40, s40, 1
	s_lshl_b32 s4, s40, 8
	s_sub_u32 s4, 128, s4
	s_sub_u32 s5, 0, s40
	s_mul_i32 s8, s40, 3968
	s_add_u32 s30, s26, s8
	s_addc_u32 s31, s27, 0
	s_add_u32 s32, s28, s8
	s_addc_u32 s33, s29, 0
	s_add_u32 s56, s30, 0x80000
	s_addc_u32 s57, s31, 0
	s_add_u32 s58, s32, 0x80000
	s_addc_u32 s59, s33, 0

; #define PG8_STAGE(bufoff, gbase, voff) do { _Pragma("unroll") for (int _i = 0; _i < 2; ++_i) \
;         __builtin_amdgcn_global_load_lds((const unsigned*)((const char*)(gbase) + (voff)[_i]), (PG8_LAS unsigned*)(lds + (bufoff) + ldsw + _i * 8192), 16, 0, 0); } while (0)
; #define PG8_LDA(dst, b, h) do { _Pragma("unroll") for (int m = 0; m < 4; ++m) _Pragma("unroll") for (int k = 0; k < 2; ++k) dst[m][k] = *(const PG8_LAS bf16x8*)(lds + PG8_SA(b, h) + aoff + m * 2048 + k * 1024); } while (0)
; #define PG8_LDB(dst, b, h) do { _Pragma("unroll") for (int n = 0; n < 2; ++n) _Pragma("unroll") for (int k = 0; k < 2; ++k) dst[n][k] = *(const PG8_LAS bf16x8*)(lds + PG8_SB(b, h) + boff + n * 2048 + k * 1024); } while (0)
; #define PG8_MMA(ai, bj, At, Bt) do { __builtin_amdgcn_s_setprio(1); _Pragma("unroll") for (int m = 0; m < 4; ++m) _Pragma("unroll") for (int n = 0; n < 2; ++n) _Pragma("unroll") for (int k = 0; k < 2; ++k) \
;         acc[ai][bj][m][n] = __builtin_amdgcn_mfma_f32_16x16x32_bf16(Bt[n][k], At[m][k], acc[ai][bj][m][n], 0, 0, 0); __builtin_amdgcn_s_setprio(0); } while (0)
; #define PG8_WAIT_V(n) asm volatile("s_waitcnt vmcnt(" #n ")" ::: "memory")
; template <class Epi, class Sched, bool ALIGN_EPI = false, bool SP2 = false>
; __device__ __forceinline__ void gemm_phase(PG8_LAS unsigned char* lds, const Gemm g, const Sched& S, const Epi& E) {
;     ...
;             PG8_LDB(B0, 0, 0); PG8_LDB(B1, 0, 1); PG8_SCHED; PG8_LDA(At, 0, 0); PG8_STAGE(PG8_SA(1, 1), a1 + hstep, voffA);
;             PG8_WAIT_V(8); PG8_WAIT_L(0); PG8_BAR; PG8_MMA(0, 0, At, B0); PG8_MMA(0, 1, At, B1); PG8_BAR; PG8_SCHED;
;             PG8_LDA(At, 0, 1); PG8_STAGE(PG8_SB(0, 0), b2, voffB); PG8_STAGE(PG8_SB(0, 1), b2 + hstep, voffB); PG8_STAGE(PG8_SA(0, 0), a2, voffA);
;             PG8_WAIT_V(8); PG8_WAIT_L(0); PG8_BAR; PG8_MMA(1, 0, At, B0); PG8_MMA(1, 1, At, B1); PG8_BAR; PG8_SCHED;
;             PG8_LDB(B0, 1, 0); PG8_LDB(B1, 1, 1); PG8_SCHED; PG8_LDA(At, 1, 0); PG8_STAGE(PG8_SA(0, 1), a2 + hstep, voffA);
;             PG8_WAIT_V(8); PG8_WAIT_L(0); PG8_BAR; PG8_MMA(0, 0, At, B0); PG8_MMA(0, 1, At, B1); PG8_BAR; PG8_SCHED;
;             PG8_LDA(At, 1, 1); PG8_STAGE(PG8_SB(1, 0), b3, voffB); PG8_STAGE(PG8_SB(1, 1), b3 + hstep, voffB); PG8_STAGE(PG8_SA(1, 0), a3, voffA);
;             PG8_WAIT_V(8); PG8_WAIT_L(0); PG8_BAR; PG8_MMA(1, 0, At, B0); PG8_MMA(1, 1, At, B1); PG8_BAR; PG8_SCHED;
.Lp4_kloop1:
	s_waitcnt vmcnt(8)
	s_waitcnt lgkmcnt(0)
	s_barrier
	v_mfma_f32_16x16x32_bf16 v[0:3], v[196:199], v[128:131], v[0:3]
	ds_read_b128 v[212:215], v247 offset:16384
	v_mfma_f32_16x16x32_bf16 v[0:3], v[200:203], v[132:135], v[0:3]
	ds_read_b128 v[216:219], v248 offset:16384
	v_mfma_f32_16x16x32_bf16 v[4:7], v[208:211], v[132:135], v[4:7]
	ds_read_b128 v[220:223], v247 offset:18432
	v_mfma_f32_16x16x32_bf16 v[4:7], v[204:207], v[128:131], v[4:7]
	ds_read_b128 v[224:227], v248 offset:18432
	v_mfma_f32_16x16x32_bf16 v[12:15], v[204:207], v[136:139], v[12:15]
	ds_read_b128 v[160:163], v245 offset:16384
	v_mfma_f32_16x16x32_bf16 v[12:15], v[208:211], v[140:143], v[12:15]
	ds_read_b128 v[164:167], v246 offset:16384
	v_mfma_f32_16x16x32_bf16 v[8:11], v[200:203], v[140:143], v[8:11]
	ds_read_b128 v[168:171], v245 offset:18432
	v_mfma_f32_16x16x32_bf16 v[8:11], v[196:199], v[136:139], v[8:11]
	ds_read_b128 v[172:175], v246 offset:18432
	v_mfma_f32_16x16x32_bf16 v[16:19], v[196:199], v[144:147], v[16:19]
	ds_read_b128 v[176:179], v245 offset:20480
	v_mfma_f32_16x16x32_bf16 v[16:19], v[200:203], v[148:151], v[16:19]
	ds_read_b128 v[180:183], v246 offset:20480
	v_mfma_f32_16x16x32_bf16 v[20:23], v[208:211], v[148:151], v[20:23]
	ds_read_b128 v[188:191], v245 offset:22528
	v_mfma_f32_16x16x32_bf16 v[20:23], v[204:207], v[144:147], v[20:23]
	ds_read_b128 v[192:195], v246 offset:22528
	v_mfma_f32_16x16x32_bf16 v[28:31], v[204:207], v[152:155], v[28:31]
	v_mfma_f32_16x16x32_bf16 v[28:31], v[208:211], v[156:159], v[28:31]
	v_mfma_f32_16x16x32_bf16 v[24:27], v[200:203], v[156:159], v[24:27]
	v_mfma_f32_16x16x32_bf16 v[24:27], v[196:199], v[152:155], v[24:27]
	s_waitcnt lgkmcnt(8)
	v_mfma_f32_16x16x32_bf16 v[32:35], v[212:215], v[128:131], v[32:35]
	v_mfma_f32_16x16x32_bf16 v[32:35], v[216:219], v[132:135], v[32:35]
	s_add_i32 m0, s35, 0x0
	v_mfma_f32_16x16x32_bf16 v[36:39], v[224:227], v[132:135], v[36:39]
	global_load_lds_dwordx4 v249, s[30:31]
	v_mfma_f32_16x16x32_bf16 v[36:39], v[220:223], v[128:131], v[36:39]
	v_mfma_f32_16x16x32_bf16 v[44:47], v[220:223], v[136:139], v[44:47]
	s_add_i32 m0, s35, 0x2000
	v_mfma_f32_16x16x32_bf16 v[44:47], v[224:227], v[140:143], v[44:47]
	global_load_lds_dwordx4 v250, s[30:31]
	v_mfma_f32_16x16x32_bf16 v[40:43], v[216:219], v[140:143], v[40:43]
	v_mfma_f32_16x16x32_bf16 v[40:43], v[212:215], v[136:139], v[40:43]
	s_add_i32 m0, s35, 0x10000
	v_mfma_f32_16x16x32_bf16 v[48:51], v[212:215], v[144:147], v[48:51]
	global_load_lds_dwordx4 v251, s[32:33]
	v_mfma_f32_16x16x32_bf16 v[48:51], v[216:219], v[148:151], v[48:51]
	v_mfma_f32_16x16x32_bf16 v[52:55], v[224:227], v[148:151], v[52:55]
	s_add_i32 m0, s35, 0x12000
	v_mfma_f32_16x16x32_bf16 v[52:55], v[220:223], v[144:147], v[52:55]
	global_load_lds_dwordx4 v252, s[32:33]
	v_mfma_f32_16x16x32_bf16 v[60:63], v[220:223], v[152:155], v[60:63]
	v_mfma_f32_16x16x32_bf16 v[60:63], v[224:227], v[156:159], v[60:63]
	v_mfma_f32_16x16x32_bf16 v[56:59], v[216:219], v[156:159], v[56:59]
	v_mfma_f32_16x16x32_bf16 v[56:59], v[212:215], v[152:155], v[56:59]
	s_waitcnt vmcnt(8)
	s_waitcnt lgkmcnt(0)
	s_barrier
	v_mfma_f32_16x16x32_bf16 v[96:99], v[212:215], v[160:163], v[96:99]
	ds_read_b128 v[128:131], v245 offset:32768
	v_mfma_f32_16x16x32_bf16 v[96:99], v[216:219], v[164:167], v[96:99]
	ds_read_b128 v[132:135], v246 offset:32768
	v_mfma_f32_16x16x32_bf16 v[100:103], v[224:227], v[164:167], v[100:103]
	ds_read_b128 v[136:139], v245 offset:34816
	v_mfma_f32_16x16x32_bf16 v[100:103], v[220:223], v[160:163], v[100:103]
	ds_read_b128 v[140:143], v246 offset:34816
	v_mfma_f32_16x16x32_bf16 v[108:111], v[220:223], v[168:171], v[108:111]
	ds_read_b128 v[144:147], v245 offset:36864
	v_mfma_f32_16x16x32_bf16 v[108:111], v[224:227], v[172:175], v[108:111]
	ds_read_b128 v[148:151], v246 offset:36864
	v_mfma_f32_16x16x32_bf16 v[104:107], v[216:219], v[172:175], v[104:107]
	ds_read_b128 v[152:155], v245 offset:38912
	v_mfma_f32_16x16x32_bf16 v[104:107], v[212:215], v[168:171], v[104:107]
	ds_read_b128 v[156:159], v246 offset:38912
	v_mfma_f32_16x16x32_bf16 v[112:115], v[212:215], v[176:179], v[112:115]
	v_mfma_f32_16x16x32_bf16 v[112:115], v[216:219], v[180:183], v[112:115]
	v_mfma_f32_16x16x32_bf16 v[116:119], v[224:227], v[180:183], v[116:119]
	v_mfma_f32_16x16x32_bf16 v[116:119], v[220:223], v[176:179], v[116:119]
	v_mfma_f32_16x16x32_bf16 v[124:127], v[220:223], v[188:191], v[124:127]
	v_mfma_f32_16x16x32_bf16 v[124:127], v[224:227], v[192:195], v[124:127]
	v_mfma_f32_16x16x32_bf16 v[120:123], v[216:219], v[192:195], v[120:123]
	v_mfma_f32_16x16x32_bf16 v[120:123], v[212:215], v[188:191], v[120:123]
	v_mfma_f32_16x16x32_bf16 v[64:67], v[196:199], v[160:163], v[64:67]
	ds_read_b128 v[212:215], v247 offset:49152
	v_mfma_f32_16x16x32_bf16 v[64:67], v[200:203], v[164:167], v[64:67]
	ds_read_b128 v[216:219], v248 offset:49152
	v_mfma_f32_16x16x32_bf16 v[68:71], v[208:211], v[164:167], v[68:71]
	ds_read_b128 v[220:223], v247 offset:51200
	v_mfma_f32_16x16x32_bf16 v[68:71], v[204:207], v[160:163], v[68:71]
	ds_read_b128 v[224:227], v248 offset:51200
	v_mfma_f32_16x16x32_bf16 v[76:79], v[204:207], v[168:171], v[76:79]
	s_add_i32 m0, s35, 0x4000
	v_mfma_f32_16x16x32_bf16 v[76:79], v[208:211], v[172:175], v[76:79]
	global_load_lds_dwordx4 v249, s[56:57]
	v_mfma_f32_16x16x32_bf16 v[72:75], v[200:203], v[172:175], v[72:75]
	s_add_i32 m0, s35, 0x6000
	v_mfma_f32_16x16x32_bf16 v[72:75], v[196:199], v[168:171], v[72:75]
	global_load_lds_dwordx4 v250, s[56:57]
	v_mfma_f32_16x16x32_bf16 v[80:83], v[196:199], v[176:179], v[80:83]
	s_add_i32 m0, s35, 0x14000
	v_mfma_f32_16x16x32_bf16 v[80:83], v[200:203], v[180:183], v[80:83]
	global_load_lds_dwordx4 v251, s[58:59]
	v_mfma_f32_16x16x32_bf16 v[84:87], v[208:211], v[180:183], v[84:87]
	s_add_i32 m0, s35, 0x16000
	v_mfma_f32_16x16x32_bf16 v[84:87], v[204:207], v[176:179], v[84:87]
	global_load_lds_dwordx4 v252, s[58:59]
	v_mfma_f32_16x16x32_bf16 v[92:95], v[204:207], v[188:191], v[92:95]
	s_add_u32 s30, s30, s4
	s_addc_u32 s31, s31, s5
	s_add_u32 s56, s56, s4
	s_addc_u32 s57, s57, s5
	v_mfma_f32_16x16x32_bf16 v[92:95], v[208:211], v[192:195], v[92:95]
	s_add_u32 s32, s32, s4
	s_addc_u32 s33, s33, s5
	s_add_u32 s58, s58, s4
	s_addc_u32 s59, s59, s5
	v_mfma_f32_16x16x32_bf16 v[88:91], v[200:203], v[192:195], v[88:91]
	v_mfma_f32_16x16x32_bf16 v[88:91], v[196:199], v[188:191], v[88:91]
	s_waitcnt vmcnt(8)
	s_waitcnt lgkmcnt(0)
	s_barrier
; #define PG8_STAGE(bufoff, gbase, voff) do { _Pragma("unroll") for (int _i = 0; _i < 2; ++_i) \
;         __builtin_amdgcn_global_load_lds((const unsigned*)((const char*)(gbase) + (voff)[_i]), (PG8_LAS unsigned*)(lds + (bufoff) + ldsw + _i * 8192), 16, 0, 0); } while (0)
; #define PG8_LDA(dst, b, h) do { _Pragma("unroll") for (int m = 0; m < 4; ++m) _Pragma("unroll") for (int k = 0; k < 2; ++k) dst[m][k] = *(const PG8_LAS bf16x8*)(lds + PG8_SA(b, h) + aoff + m * 2048 + k * 1024); } while (0)
; #define PG8_WAIT_V(n) asm volatile("s_waitcnt vmcnt(" #n ")" ::: "memory")
; template <class Epi, class Sched, bool ALIGN_EPI = false, bool SP2 = false>
; __device__ __forceinline__ void gemm_phase(PG8_LAS unsigned char* lds, const Gemm g, const Sched& S, const Epi& E) {
;     ...
;         const bool has_next = S.next(ui + 1, nxt);
;         const char* nA = has_next ? (const char*)g.A + (size_t)nxt.pm * tstep : cA; const char* nB = has_next ? (const char*)g.Bt + (size_t)nxt.pn * tstep : cB;
;         for (int t = 0; t < nt; t += 2) {
;             const bool last = (t == nt - 2);
;             const char* a1 = cA + (size_t)(t + 1) * kstep;
;             const char* a2 = last ? nA : cA + (size_t)(t + 2) * kstep; const char* b2 = last ? nB : cB + (size_t)(t + 2) * kstep;
;             const char* a3 = a2 + kstep; const char* b3 = b2 + kstep;
;     ...
;             PG8_LDB(B0, 0, 0); PG8_LDB(B1, 0, 1); PG8_SCHED; PG8_LDA(At, 0, 0); PG8_STAGE(PG8_SA(1, 1), a1 + hstep, voffA);
;             PG8_WAIT_V(8); PG8_WAIT_L(0); PG8_BAR; PG8_MMA(0, 0, At, B0); PG8_MMA(0, 1, At, B1); PG8_BAR; PG8_SCHED;
;             PG8_LDA(At, 0, 1); PG8_STAGE(PG8_SB(0, 0), b2, voffB); PG8_STAGE(PG8_SB(0, 1), b2 + hstep, voffB); PG8_STAGE(PG8_SA(0, 0), a2, voffA);
;             PG8_WAIT_V(8); PG8_WAIT_L(0); PG8_BAR; PG8_MMA(1, 0, At, B0); PG8_MMA(1, 1, At, B1); PG8_BAR; PG8_SCHED;
;             PG8_LDB(B0, 1, 0); PG8_LDB(B1, 1, 1); PG8_SCHED; PG8_LDA(At, 1, 0); PG8_STAGE(PG8_SA(0, 1), a2 + hstep, voffA);
;             PG8_WAIT_V(8); PG8_WAIT_L(0); PG8_BAR; PG8_MMA(0, 0, At, B0); PG8_MMA(0, 1, At, B1); PG8_BAR; PG8_SCHED;
;             PG8_LDA(At, 1, 1); PG8_STAGE(PG8_SB(1, 0), b3, voffB); PG8_STAGE(PG8_SB(1, 1), b3 + hstep, voffB); PG8_STAGE(PG8_SA(1, 0), a3, voffA);
;             PG8_WAIT_V(8); PG8_WAIT_L(0); PG8_BAR; PG8_MMA(1, 0, At, B0); PG8_MMA(1, 1, At, B1); PG8_BAR; PG8_SCHED;
	v_mfma_f32_16x16x32_bf16 v[32:35], v[212:215], v[128:131], v[32:35]
	ds_read_b128 v[196:199], v247 offset:32768
	v_mfma_f32_16x16x32_bf16 v[32:35], v[216:219], v[132:135], v[32:35]
	ds_read_b128 v[200:203], v248 offset:32768
	v_mfma_f32_16x16x32_bf16 v[36:39], v[224:227], v[132:135], v[36:39]
	ds_read_b128 v[204:207], v247 offset:34816
	v_mfma_f32_16x16x32_bf16 v[36:39], v[220:223], v[128:131], v[36:39]
	ds_read_b128 v[208:211], v248 offset:34816
	v_mfma_f32_16x16x32_bf16 v[44:47], v[220:223], v[136:139], v[44:47]
	ds_read_b128 v[160:163], v245 offset:49152
	v_mfma_f32_16x16x32_bf16 v[44:47], v[224:227], v[140:143], v[44:47]
	ds_read_b128 v[164:167], v246 offset:49152
	v_mfma_f32_16x16x32_bf16 v[40:43], v[216:219], v[140:143], v[40:43]
	ds_read_b128 v[168:171], v245 offset:51200
	v_mfma_f32_16x16x32_bf16 v[40:43], v[212:215], v[136:139], v[40:43]
	ds_read_b128 v[172:175], v246 offset:51200
	v_mfma_f32_16x16x32_bf16 v[48:51], v[212:215], v[144:147], v[48:51]
	ds_read_b128 v[176:179], v245 offset:53248
	v_mfma_f32_16x16x32_bf16 v[48:51], v[216:219], v[148:151], v[48:51]
	ds_read_b128 v[180:183], v246 offset:53248
	v_mfma_f32_16x16x32_bf16 v[52:55], v[224:227], v[148:151], v[52:55]
	ds_read_b128 v[188:191], v245 offset:55296
	v_mfma_f32_16x16x32_bf16 v[52:55], v[220:223], v[144:147], v[52:55]
	ds_read_b128 v[192:195], v246 offset:55296
	v_mfma_f32_16x16x32_bf16 v[60:63], v[220:223], v[152:155], v[60:63]
	v_mfma_f32_16x16x32_bf16 v[60:63], v[224:227], v[156:159], v[60:63]
	v_mfma_f32_16x16x32_bf16 v[56:59], v[216:219], v[156:159], v[56:59]
	v_mfma_f32_16x16x32_bf16 v[56:59], v[212:215], v[152:155], v[56:59]
	s_waitcnt lgkmcnt(8)
	v_mfma_f32_16x16x32_bf16 v[0:3], v[196:199], v[128:131], v[0:3]
	v_mfma_f32_16x16x32_bf16 v[0:3], v[200:203], v[132:135], v[0:3]
	s_add_i32 m0, s35, 0x8000
	v_mfma_f32_16x16x32_bf16 v[4:7], v[208:211], v[132:135], v[4:7]
	global_load_lds_dwordx4 v249, s[30:31]
	v_mfma_f32_16x16x32_bf16 v[4:7], v[204:207], v[128:131], v[4:7]
	v_mfma_f32_16x16x32_bf16 v[12:15], v[204:207], v[136:139], v[12:15]
	s_add_i32 m0, s35, 0xa000
	v_mfma_f32_16x16x32_bf16 v[12:15], v[208:211], v[140:143], v[12:15]
	global_load_lds_dwordx4 v250, s[30:31]
	v_mfma_f32_16x16x32_bf16 v[8:11], v[200:203], v[140:143], v[8:11]
	v_mfma_f32_16x16x32_bf16 v[8:11], v[196:199], v[136:139], v[8:11]
	s_add_i32 m0, s35, 0x1c000
	v_mfma_f32_16x16x32_bf16 v[16:19], v[196:199], v[144:147], v[16:19]
	global_load_lds_dwordx4 v251, s[58:59]
	v_mfma_f32_16x16x32_bf16 v[16:19], v[200:203], v[148:151], v[16:19]
	v_mfma_f32_16x16x32_bf16 v[20:23], v[208:211], v[148:151], v[20:23]
	s_add_i32 m0, s35, 0x1e000
	v_mfma_f32_16x16x32_bf16 v[20:23], v[204:207], v[144:147], v[20:23]
	global_load_lds_dwordx4 v252, s[58:59]
	v_mfma_f32_16x16x32_bf16 v[28:31], v[204:207], v[152:155], v[28:31]
	v_mfma_f32_16x16x32_bf16 v[28:31], v[208:211], v[156:159], v[28:31]
	v_mfma_f32_16x16x32_bf16 v[24:27], v[200:203], v[156:159], v[24:27]
	v_mfma_f32_16x16x32_bf16 v[24:27], v[196:199], v[152:155], v[24:27]
	s_waitcnt vmcnt(8)
	s_waitcnt lgkmcnt(0)
	s_barrier
	v_mfma_f32_16x16x32_bf16 v[64:67], v[196:199], v[160:163], v[64:67]
	ds_read_b128 v[128:131], v245 offset:0
	v_mfma_f32_16x16x32_bf16 v[64:67], v[200:203], v[164:167], v[64:67]
	ds_read_b128 v[132:135], v246 offset:0
	v_mfma_f32_16x16x32_bf16 v[68:71], v[208:211], v[164:167], v[68:71]
	ds_read_b128 v[136:139], v245 offset:2048
	v_mfma_f32_16x16x32_bf16 v[68:71], v[204:207], v[160:163], v[68:71]
	ds_read_b128 v[140:143], v246 offset:2048
	v_mfma_f32_16x16x32_bf16 v[76:79], v[204:207], v[168:171], v[76:79]
	ds_read_b128 v[144:147], v245 offset:4096
	v_mfma_f32_16x16x32_bf16 v[76:79], v[208:211], v[172:175], v[76:79]
	ds_read_b128 v[148:151], v246 offset:4096
	v_mfma_f32_16x16x32_bf16 v[72:75], v[200:203], v[172:175], v[72:75]
	ds_read_b128 v[152:155], v245 offset:6144
	v_mfma_f32_16x16x32_bf16 v[72:75], v[196:199], v[168:171], v[72:75]
	ds_read_b128 v[156:159], v246 offset:6144
	v_mfma_f32_16x16x32_bf16 v[80:83], v[196:199], v[176:179], v[80:83]
	v_mfma_f32_16x16x32_bf16 v[80:83], v[200:203], v[180:183], v[80:83]
	v_mfma_f32_16x16x32_bf16 v[84:87], v[208:211], v[180:183], v[84:87]
	v_mfma_f32_16x16x32_bf16 v[84:87], v[204:207], v[176:179], v[84:87]
	v_mfma_f32_16x16x32_bf16 v[92:95], v[204:207], v[188:191], v[92:95]
	v_mfma_f32_16x16x32_bf16 v[92:95], v[208:211], v[192:195], v[92:95]
	v_mfma_f32_16x16x32_bf16 v[88:91], v[200:203], v[192:195], v[88:91]
	v_mfma_f32_16x16x32_bf16 v[88:91], v[196:199], v[188:191], v[88:91]
	v_mfma_f32_16x16x32_bf16 v[96:99], v[212:215], v[160:163], v[96:99]
	ds_read_b128 v[196:199], v247 offset:0
	v_mfma_f32_16x16x32_bf16 v[96:99], v[216:219], v[164:167], v[96:99]
	ds_read_b128 v[200:203], v248 offset:0
	v_mfma_f32_16x16x32_bf16 v[100:103], v[224:227], v[164:167], v[100:103]
	ds_read_b128 v[204:207], v247 offset:2048
	v_mfma_f32_16x16x32_bf16 v[100:103], v[220:223], v[160:163], v[100:103]
	ds_read_b128 v[208:211], v248 offset:2048
	v_mfma_f32_16x16x32_bf16 v[108:111], v[220:223], v[168:171], v[108:111]
	s_add_i32 m0, s35, 0xc000
	v_mfma_f32_16x16x32_bf16 v[108:111], v[224:227], v[172:175], v[108:111]
	global_load_lds_dwordx4 v249, s[56:57]
	v_mfma_f32_16x16x32_bf16 v[104:107], v[216:219], v[172:175], v[104:107]
	s_add_i32 m0, s35, 0xe000
	v_mfma_f32_16x16x32_bf16 v[104:107], v[212:215], v[168:171], v[104:107]
	global_load_lds_dwordx4 v250, s[56:57]
	v_mfma_f32_16x16x32_bf16 v[112:115], v[212:215], v[176:179], v[112:115]
	s_add_i32 m0, s35, 0x18000
	v_mfma_f32_16x16x32_bf16 v[112:115], v[216:219], v[180:183], v[112:115]
	global_load_lds_dwordx4 v251, s[32:33]
	v_mfma_f32_16x16x32_bf16 v[116:119], v[224:227], v[180:183], v[116:119]
	s_add_i32 m0, s35, 0x1a000
	v_mfma_f32_16x16x32_bf16 v[116:119], v[220:223], v[176:179], v[116:119]
	global_load_lds_dwordx4 v252, s[32:33]
	v_mfma_f32_16x16x32_bf16 v[124:127], v[220:223], v[188:191], v[124:127]
	s_add_u32 s30, s30, s4
	s_addc_u32 s31, s31, s5
	s_add_u32 s56, s56, s4
	s_addc_u32 s57, s57, s5
	v_mfma_f32_16x16x32_bf16 v[124:127], v[224:227], v[192:195], v[124:127]
	s_add_u32 s32, s32, s4
	s_addc_u32 s33, s33, s5
	s_add_u32 s58, s58, s4
	s_addc_u32 s59, s59, s5
	v_mfma_f32_16x16x32_bf16 v[120:123], v[216:219], v[192:195], v[120:123]
	v_mfma_f32_16x16x32_bf16 v[120:123], v[212:215], v[188:191], v[120:123]
	s_add_i32 s34, s34, -1
	s_cmp_lg_u32 s34, 1
	s_cbranch_scc1 .Lp4_nosw1
	s_add_u32 s45, s16, 1
	s_and_b32 s40, s45, 1
	s_xor_b32 s40, s40, 1
	s_lshl_b32 s4, s40, 8
	s_sub_u32 s4, 128, s4
	s_sub_u32 s5, 0, s40
	s_mul_i32 s8, s40, 3968
	s_add_u32 s30, s26, s8
	s_addc_u32 s31, s27, 0
	s_add_u32 s32, s28, s8
	s_addc_u32 s33, s29, 0
	s_add_u32 s56, s30, 0x80000
	s_addc_u32 s57, s31, 0
	s_add_u32 s58, s32, 0x80000
	s_addc_u32 s59, s33, 0
